# diff-attention A half-trip: row-sum with v_pk_add_f32 on 14 adjacent probability pairs (14 fewer VALU per half-trip), same f32 adds as the B half already uses
# baseline (speedup 1.0000x reference)
; #define DA_WAIT_BAR(N) do { asm volatile("s_waitcnt vmcnt(" #N ")" ::: "memory"); __builtin_amdgcn_s_barrier(); } while (0)
; __device__ __forceinline__ void dattn_unit(LAS unsigned char* lds, const bf16_t* Qp, const bf16_t* Kp, const bf16_t* Vtp, int qb, bf16_t* Op, const float* lq1, const float* lk1, const float* lq2, const float* lk2, const float* subg, float outscale, int tid) {
;     ...
;         DA_WAIT_BAR(4); DA_DMA(kt + 3, (kt + 3) & 3); DA_QK(sb, mrb, (kt + 1) & 3); DA_SOFTMAX_PV(sa, mra, kt & 3, false, kt);
;         DA_WAIT_BAR(4); if (kt + 4 < nk) DA_DMA(kt + 4, kt & 3); DA_QK(sa, mra, (kt + 2) & 3); DA_SOFTMAX_PV(sb, mrb, (kt + 1) & 3, false, kt + 1);
.LBB0_218:
	v_exp_f32_e32 v198, v98
	v_exp_f32_e32 v0, v99
	v_exp_f32_e32 v200, v100
	v_exp_f32_e32 v98, v101
	v_exp_f32_e32 v238, v102
	v_exp_f32_e32 v99, v103
	v_exp_f32_e32 v239, v104
	v_exp_f32_e32 v100, v105
	v_cvt_pk_bf16_f32 v240, v198, v0
	v_cvt_pk_bf16_f32 v241, v200, v98
	v_cvt_pk_bf16_f32 v242, v238, v99
	v_cvt_pk_bf16_f32 v243, v239, v100
	v_exp_f32_e32 v105, v106
	s_waitcnt lgkmcnt(0)
	v_mfma_f32_32x32x16_bf16 v[50:65], v[194:197], v[240:243], v[50:65]
	v_add_u32_e32 v213, s7, v219
	v_exp_f32_e32 v101, v107
	v_exp_f32_e32 v106, v108
	v_exp_f32_e32 v102, v109
	v_mfma_f32_32x32x16_bf16 v[34:49], v[76:79], v[240:243], v[34:49]
	s_add_i32 m0, s98, 0x2000
	s_nop 0
	global_load_lds_dwordx4 v204, s[100:101]
	v_exp_f32_e32 v107, v110
	v_exp_f32_e32 v103, v111
	v_exp_f32_e32 v108, v112
	v_mfma_f32_32x32x16_bf16 v[18:33], v[72:75], v[240:243], v[18:33]
	ds_read_b128 v[72:75], v213
	ds_read_b128 v[76:79], v213 offset:4096
	ds_read_b128 v[194:197], v213 offset:8192
	ds_read_b128 v[220:223], v213 offset:12288
	v_exp_f32_e32 v104, v113
	v_cvt_pk_bf16_f32 v244, v105, v101
	v_cvt_pk_bf16_f32 v245, v106, v102
	v_mfma_f32_32x32x16_bf16 v[2:17], v[68:71], v[240:243], v[2:17]
	v_cvt_pk_bf16_f32 v246, v107, v103
	v_cvt_pk_bf16_f32 v247, v108, v104
	v_exp_f32_e32 v109, v82
	v_exp_f32_e32 v82, v83
	s_waitcnt lgkmcnt(0)
	v_mfma_f32_32x32x16_bf16 v[50:65], v[72:75], v[244:247], v[50:65]
	v_add_u32_e32 v214, s7, v218
	v_exp_f32_e32 v110, v84
	v_exp_f32_e32 v83, v85
	v_exp_f32_e32 v111, v86
	v_mfma_f32_32x32x16_bf16 v[34:49], v[76:79], v[244:247], v[34:49]
	s_add_i32 m0, s99, 0x2000
	s_nop 0
	global_load_lds_dwordx4 v202, s[34:35]
	v_exp_f32_e32 v84, v87
	v_exp_f32_e32 v112, v88
	v_exp_f32_e32 v85, v89
	v_mfma_f32_32x32x16_bf16 v[18:33], v[194:197], v[244:247], v[18:33]
	ds_read_b128 v[68:71], v214
	ds_read_b128 v[72:75], v214 offset:4096
	ds_read_b128 v[76:79], v214 offset:8192
	ds_read_b128 v[194:197], v214 offset:12288
	v_exp_f32_e32 v90, v90
	v_exp_f32_e32 v86, v91
	v_exp_f32_e32 v91, v92
	v_mfma_f32_32x32x16_bf16 v[2:17], v[220:223], v[244:247], v[2:17]
	v_exp_f32_e32 v87, v93
	v_exp_f32_e32 v92, v94
	v_exp_f32_e32 v88, v95
	v_exp_f32_e32 v93, v96
	v_exp_f32_e32 v89, v97
	v_cvt_pk_bf16_f32 v94, v109, v82
	v_cvt_pk_bf16_f32 v95, v110, v83
	v_cvt_pk_bf16_f32 v96, v111, v84
	v_cvt_pk_bf16_f32 v97, v112, v85
	v_add_f32_e32 v240, 0, v198
	v_add_f32_e32 v241, 0, v0
	s_waitcnt lgkmcnt(0)
	v_mfma_f32_32x32x16_bf16 v[50:65], v[68:71], v[94:97], v[50:65]
	v_add_u32_e32 v215, s7, v217
	v_cvt_pk_bf16_f32 v248, v90, v86
	v_cvt_pk_bf16_f32 v249, v91, v87
	v_add_f32_e32 v240, v200, v240
	v_mfma_f32_32x32x16_bf16 v[34:49], v[72:75], v[94:97], v[34:49]
	v_cvt_pk_bf16_f32 v250, v92, v88
	v_cvt_pk_bf16_f32 v251, v93, v89
	v_pk_add_f32 v[240:241], v[98:99], v[240:241]
	v_pk_add_f32 v[240:241], v[238:239], v[240:241]
	v_mfma_f32_32x32x16_bf16 v[18:33], v[76:79], v[94:97], v[18:33]
	ds_read_b128 v[68:71], v215
	ds_read_b128 v[72:75], v215 offset:4096
	ds_read_b128 v[76:79], v215 offset:8192
	ds_read_b128 v[220:223], v215 offset:12288
	v_pk_add_f32 v[240:241], v[100:101], v[240:241]
	v_mfma_f32_32x32x16_bf16 v[2:17], v[194:197], v[94:97], v[2:17]
	v_pk_add_f32 v[240:241], v[106:107], v[240:241]
	v_pk_add_f32 v[240:241], v[102:103], v[240:241]
	v_pk_add_f32 v[240:241], v[104:105], v[240:241]
	v_pk_add_f32 v[240:241], v[108:109], v[240:241]
	s_waitcnt lgkmcnt(0)
	v_mfma_f32_32x32x16_bf16 v[50:65], v[68:71], v[248:251], v[50:65]
	v_pk_add_f32 v[240:241], v[82:83], v[240:241]
	v_pk_add_f32 v[240:241], v[110:111], v[240:241]
	v_add_f32_e32 v240, v112, v240
	v_pk_add_f32 v[240:241], v[84:85], v[240:241]
	v_mfma_f32_32x32x16_bf16 v[34:49], v[72:75], v[248:251], v[34:49]
	v_pk_add_f32 v[240:241], v[90:91], v[240:241]
	v_pk_add_f32 v[240:241], v[86:87], v[240:241]
	v_mfma_f32_32x32x16_bf16 v[18:33], v[76:79], v[248:251], v[18:33]
	v_pk_add_f32 v[240:241], v[92:93], v[240:241]
	v_pk_add_f32 v[240:241], v[88:89], v[240:241]
	v_add_f32_e32 v0, v241, v240
	v_add_f32_e32 v0, v232, v0
	v_mfma_f32_32x32x16_bf16 v[2:17], v[220:223], v[248:251], v[2:17]
	s_waitcnt vmcnt(4)
	s_add_i32 s17, s4, 4
	s_cmp_gt_u32 s17, s11
	s_barrier
	s_cbranch_scc1 .LBB0_220
	s_add_i32 s17, s15, s6
	s_add_i32 s7, s7, s14
	s_add_u32 s100, s74, s22
	s_addc_u32 s101, s75, s23
	s_add_u32 s34, s74, 0x20400200
	s_addc_u32 s35, s75, 0
	s_mov_b32 m0, s17
	s_nop 0
	global_load_lds_dwordx4 v206, s[100:101]
	s_mov_b32 m0, s7
	s_nop 0
	global_load_lds_dwordx4 v80, s[34:35]
	s_add_i32 m0, s17, 0x2000
	s_nop 0
	global_load_lds_dwordx4 v204, s[100:101]
	s_add_i32 m0, s7, 0x2000
	s_nop 0
	global_load_lds_dwordx4 v202, s[34:35]
